# row-max exchange across lane halves in C pair and A tiles: ds_bpermute (lane xor 32) + address calc replaced by v_permlane32_swap
# speedup vs baseline: 1.0059x; 1.0018x over previous
.LBB0_168:
	v_mul_f32_e32 v76, 0x3fb8aa3b, v49
	v_mul_f32_e32 v77, 0x3fb8aa3b, v48
	v_mul_f32_e32 v75, 0x3fb8aa3b, v50
	v_mul_f32_e32 v74, 0x3fb8aa3b, v51
	v_mul_f32_e32 v73, 0x3fb8aa3b, v52
	v_mul_f32_e32 v71, 0x3fb8aa3b, v53
	v_mul_f32_e32 v69, 0x3fb8aa3b, v54
	v_mul_f32_e32 v67, 0x3fb8aa3b, v55
	v_mul_f32_e32 v66, 0x3fb8aa3b, v56
	v_mul_f32_e32 v68, 0x3fb8aa3b, v57
	v_mul_f32_e32 v70, 0x3fb8aa3b, v58
	v_mul_f32_e32 v72, 0x3fb8aa3b, v59
	v_mul_f32_e32 v51, 0x3fb8aa3b, v60
	v_mul_f32_e32 v50, 0x3fb8aa3b, v61
	v_mul_f32_e32 v49, 0x3fb8aa3b, v62
	v_mul_f32_e32 v48, 0x3fb8aa3b, v63
	v_max3_f32 v0, v65, v76, v14
	v_max3_f32 v0, v0, v15, v77
	v_max3_f32 v0, v0, v64, v75
	v_max3_f32 v0, v0, v74, v12
	v_max3_f32 v0, v0, v13, v73
	v_max3_f32 v0, v0, v71, v10
	v_max3_f32 v0, v0, v11, v69
	v_max3_f32 v0, v0, v67, v8
	v_max3_f32 v0, v0, v9, v66
	v_max3_f32 v0, v0, v68, v6
	v_max3_f32 v0, v0, v7, v70
	v_max3_f32 v0, v0, v72, v4
	v_max3_f32 v0, v0, v5, v51
	v_max3_f32 v0, v0, v50, v2
	v_max3_f32 v0, v0, v3, v49
	v_max3_f32 v0, v0, v48, v48
	v_mov_b32_e32 v52, v0
	s_nop 1
	v_permlane32_swap_b32_e32 v52, v0
	s_waitcnt lgkmcnt(0)
	v_max3_f32 v52, v118, v0, v52
	v_sub_f32_e32 v0, v118, v52
	v_exp_f32_e32 v0, v0
	s_nop 0
	v_cmp_eq_f32_e32 vcc, 1.0, v0
	s_cmp_eq_u64 vcc, exec
	s_cbranch_scc1 .LBB0_170
	v_pk_mul_f32 v[46:47], v[46:47], v[0:1] op_sel_hi:[1,0]
	v_pk_mul_f32 v[44:45], v[44:45], v[0:1] op_sel_hi:[1,0]
	v_pk_mul_f32 v[42:43], v[42:43], v[0:1] op_sel_hi:[1,0]
	v_pk_mul_f32 v[40:41], v[40:41], v[0:1] op_sel_hi:[1,0]
	v_pk_mul_f32 v[38:39], v[38:39], v[0:1] op_sel_hi:[1,0]
	v_pk_mul_f32 v[36:37], v[36:37], v[0:1] op_sel_hi:[1,0]
	v_pk_mul_f32 v[34:35], v[34:35], v[0:1] op_sel_hi:[1,0]
	v_pk_mul_f32 v[32:33], v[32:33], v[0:1] op_sel_hi:[1,0]
	v_pk_mul_f32 v[30:31], v[30:31], v[0:1] op_sel_hi:[1,0]
	v_pk_mul_f32 v[28:29], v[28:29], v[0:1] op_sel_hi:[1,0]
	v_pk_mul_f32 v[26:27], v[26:27], v[0:1] op_sel_hi:[1,0]
	v_pk_mul_f32 v[24:25], v[24:25], v[0:1] op_sel_hi:[1,0]
	v_pk_mul_f32 v[22:23], v[22:23], v[0:1] op_sel_hi:[1,0]
	v_pk_mul_f32 v[20:21], v[20:21], v[0:1] op_sel_hi:[1,0]
	v_pk_mul_f32 v[18:19], v[18:19], v[0:1] op_sel_hi:[1,0]
	v_pk_mul_f32 v[16:17], v[16:17], v[0:1] op_sel_hi:[1,0]

.LBB0_726:
	v_max3_f32 v0, v37, v35, v40
	v_max3_f32 v0, v0, v38, v41
	v_max3_f32 v0, v0, v39, v34
	v_max3_f32 v0, v0, v36, v44
	v_max3_f32 v0, v0, v42, v45
	v_max3_f32 v0, v0, v43, v48
	v_max3_f32 v0, v0, v46, v49
	v_max3_f32 v0, v0, v47, v52
	v_max3_f32 v0, v0, v50, v53
	v_max3_f32 v0, v0, v51, v60
	v_max3_f32 v0, v0, v54, v61
	v_max3_f32 v0, v0, v55, v58
	v_max3_f32 v0, v0, v56, v59
	v_max3_f32 v0, v0, v57, v64
	v_max3_f32 v0, v0, v62, v65
	v_max3_f32 v0, v0, v63, v63
	s_mov_b32 s18, 0xff800000
	v_mov_b32_e32 v2, v0
	s_nop 1
	v_permlane32_swap_b32_e32 v2, v0
	s_waitcnt lgkmcnt(0)
	v_max3_f32 v225, v0, v2, s18
	v_sub_f32_e32 v3, v38, v225
	v_exp_f32_e32 v67, v3
	v_sub_f32_e32 v3, v40, v225
	v_exp_f32_e32 v73, v3
	v_sub_f32_e32 v3, v39, v225
	v_exp_f32_e32 v66, v3
	v_sub_f32_e32 v3, v41, v225
	v_exp_f32_e32 v72, v3
	v_sub_f32_e32 v3, v42, v225
	v_exp_f32_e32 v69, v3
	v_sub_f32_e32 v3, v44, v225
	v_exp_f32_e32 v75, v3
	v_sub_f32_e32 v3, v43, v225
	v_exp_f32_e32 v68, v3
	v_sub_f32_e32 v3, v45, v225
	v_exp_f32_e32 v74, v3
	v_sub_f32_e32 v3, v46, v225
	v_exp_f32_e32 v77, v3
	v_sub_f32_e32 v3, v48, v225
	v_sub_f32_e32 v2, 0xff800000, v225
	v_exp_f32_e32 v177, v3
	v_sub_f32_e32 v3, v47, v225
	v_exp_f32_e32 v70, v3
	v_sub_f32_e32 v3, v49, v225
	v_exp_f32_e32 v178, v2
	v_exp_f32_e32 v76, v3
	v_sub_f32_e32 v3, v50, v225
	v_exp_f32_e32 v79, v3
	v_sub_f32_e32 v3, v52, v225
	v_exp_f32_e32 v179, v3
	v_sub_f32_e32 v3, v51, v225
	v_exp_f32_e32 v52, v3
	v_sub_f32_e32 v3, v53, v225
	v_cmp_eq_f32_e32 vcc, 1.0, v178
	v_exp_f32_e32 v78, v3
	v_sub_f32_e32 v3, v54, v225
	v_sub_f32_e32 v2, v56, v225
	s_cmp_lg_u64 vcc, exec
	v_sub_f32_e32 v0, v34, v225
	v_exp_f32_e32 v151, v3
	v_sub_f32_e32 v3, v60, v225
	v_exp_f32_e32 v181, v2
	v_mul_f32_e32 v2, 0, v178
	s_cselect_b64 vcc, -1, 0
	v_exp_f32_e32 v15, v0
	v_sub_f32_e32 v0, v36, v225
	v_exp_f32_e32 v180, v3
	v_sub_f32_e32 v3, v55, v225
	v_cndmask_b32_e32 v16, 0, v2, vcc
	v_exp_f32_e32 v71, v0
	v_sub_f32_e32 v0, v35, v225
	v_exp_f32_e32 v54, v3
	v_sub_f32_e32 v3, v61, v225
	v_mov_b32_e32 v17, v16
	v_mov_b32_e32 v18, v16
	v_mov_b32_e32 v19, v16
	v_mov_b32_e32 v20, v16
	v_mov_b32_e32 v21, v16
	v_mov_b32_e32 v22, v16
	v_mov_b32_e32 v23, v16
	v_mov_b32_e32 v24, v16
	v_mov_b32_e32 v25, v16
	v_mov_b32_e32 v26, v16
	v_mov_b32_e32 v27, v16
	v_mov_b32_e32 v28, v16
	v_mov_b32_e32 v29, v16
	v_mov_b32_e32 v30, v16
	v_mov_b32_e32 v31, v16
	v_exp_f32_e32 v14, v0
	v_sub_f32_e32 v0, v37, v225
	v_exp_f32_e32 v60, v3
	ds_read_b64_tr_b16 v[232:233], v205 offset:0
	ds_read_b64_tr_b16 v[234:235], v205 offset:1536
	ds_read_b64_tr_b16 v[228:229], v205 offset:64
	ds_read_b64_tr_b16 v[230:231], v205 offset:1600
	ds_read_b64_tr_b16 v[188:189], v205 offset:3072
	ds_read_b64_tr_b16 v[190:191], v205 offset:4608
	ds_read_b64_tr_b16 v[184:185], v205 offset:3136
	ds_read_b64_tr_b16 v[186:187], v205 offset:4672
	ds_read_b64_tr_b16 v[48:49], v205 offset:6144
	ds_read_b64_tr_b16 v[50:51], v205 offset:7680
	ds_read_b64_tr_b16 v[10:11], v205 offset:6208
	ds_read_b64_tr_b16 v[12:13], v205 offset:7744
	ds_read_b64_tr_b16 v[6:7], v205 offset:9216
	ds_read_b64_tr_b16 v[8:9], v205 offset:10752
	ds_read_b64_tr_b16 v[2:3], v205 offset:9280
	ds_read_b64_tr_b16 v[4:5], v205 offset:10816
	s_waitcnt lgkmcnt(0)
	v_cvt_pk_bf16_f32 v236, v15, v14
	v_cvt_pk_bf16_f32 v237, v67, v66
	v_cvt_pk_bf16_f32 v238, v69, v68
	v_cvt_pk_bf16_f32 v239, v77, v70
	v_sub_f32_e32 v53, v58, v225
	v_mfma_f32_32x32x16_bf16 v[32:47], v[232:235], v[236:239], v[16:31]
	v_exp_f32_e32 v182, v53
	v_sub_f32_e32 v53, v57, v225
	v_exp_f32_e32 v56, v53
	v_sub_f32_e32 v53, v59, v225
	v_exp_f32_e32 v176, v53
	v_sub_f32_e32 v53, v62, v225
	v_exp_f32_e32 v59, v53
	v_mfma_f32_32x32x16_bf16 v[16:31], v[228:231], v[236:239], v[16:31]
	v_sub_f32_e32 v53, v63, v225
	v_exp_f32_e32 v58, v53
	v_cvt_pk_bf16_f32 v228, v79, v52
	v_cvt_pk_bf16_f32 v229, v151, v54
	v_cvt_pk_bf16_f32 v230, v181, v56
	v_cvt_pk_bf16_f32 v231, v59, v58
	v_sub_f32_e32 v53, v64, v225
	v_mfma_f32_32x32x16_bf16 v[32:47], v[188:191], v[228:231], v[32:47]
	v_exp_f32_e32 v63, v53
	v_sub_f32_e32 v53, v65, v225
	v_exp_f32_e32 v0, v0
	v_exp_f32_e32 v62, v53
	s_andn2_b64 vcc, exec, s[16:17]
	v_mfma_f32_32x32x16_bf16 v[16:31], v[184:187], v[228:231], v[16:31]
	s_cbranch_vccnz .LBB0_728
	v_cvt_pk_bf16_f32 v184, v71, v0
	v_cvt_pk_bf16_f32 v185, v73, v72
	v_cvt_pk_bf16_f32 v186, v75, v74
	v_cvt_pk_bf16_f32 v187, v177, v76
	s_nop 0
	v_mfma_f32_32x32x16_bf16 v[32:47], v[48:51], v[184:187], v[32:47]
	v_mfma_f32_32x32x16_bf16 v[16:31], v[10:13], v[184:187], v[16:31]
	v_cvt_pk_bf16_f32 v10, v179, v78
	v_cvt_pk_bf16_f32 v11, v180, v60
	v_cvt_pk_bf16_f32 v12, v182, v176
	v_cvt_pk_bf16_f32 v13, v63, v62
	s_nop 0
	v_mfma_f32_32x32x16_bf16 v[32:47], v[6:9], v[10:13], v[32:47]
	v_mfma_f32_32x32x16_bf16 v[16:31], v[2:5], v[10:13], v[16:31]

.LBB0_746:
	v_max3_f32 v0, v5, v3, v8
	v_max3_f32 v0, v0, v6, v9
	v_max3_f32 v0, v0, v7, v2
	v_max3_f32 v0, v0, v4, v12
	v_max3_f32 v0, v0, v10, v13
	v_max3_f32 v0, v0, v11, v176
	v_max3_f32 v0, v0, v14, v177
	v_max3_f32 v0, v0, v15, v180
	v_max3_f32 v0, v0, v178, v181
	v_max3_f32 v0, v0, v179, v184
	v_max3_f32 v0, v0, v182, v185
	v_max3_f32 v0, v0, v183, v188
	v_max3_f32 v0, v0, v186, v189
	v_max3_f32 v0, v0, v187, v192
	v_max3_f32 v0, v0, v190, v193
	v_max3_f32 v0, v0, v191, v191
	v_mov_b32_e32 v48, v0
	s_nop 1
	v_permlane32_swap_b32_e32 v48, v0
	s_waitcnt lgkmcnt(0)
	v_max3_f32 v52, v225, v0, v48
	v_sub_f32_e32 v0, v225, v52
	v_exp_f32_e32 v0, v0
	s_nop 0
	v_cmp_eq_f32_e32 vcc, 1.0, v0
	s_cmp_eq_u64 vcc, exec
	s_cbranch_scc1 .LBB0_748
	v_pk_mul_f32 v[46:47], v[46:47], v[0:1] op_sel_hi:[1,0]
	v_pk_mul_f32 v[44:45], v[44:45], v[0:1] op_sel_hi:[1,0]
	v_pk_mul_f32 v[42:43], v[42:43], v[0:1] op_sel_hi:[1,0]
	v_pk_mul_f32 v[40:41], v[40:41], v[0:1] op_sel_hi:[1,0]
	v_pk_mul_f32 v[38:39], v[38:39], v[0:1] op_sel_hi:[1,0]
	v_pk_mul_f32 v[36:37], v[36:37], v[0:1] op_sel_hi:[1,0]
	v_pk_mul_f32 v[34:35], v[34:35], v[0:1] op_sel_hi:[1,0]
	v_pk_mul_f32 v[32:33], v[32:33], v[0:1] op_sel_hi:[1,0]
	v_pk_mul_f32 v[30:31], v[30:31], v[0:1] op_sel_hi:[1,0]
	v_pk_mul_f32 v[28:29], v[28:29], v[0:1] op_sel_hi:[1,0]
	v_pk_mul_f32 v[26:27], v[26:27], v[0:1] op_sel_hi:[1,0]
	v_pk_mul_f32 v[24:25], v[24:25], v[0:1] op_sel_hi:[1,0]
	v_pk_mul_f32 v[22:23], v[22:23], v[0:1] op_sel_hi:[1,0]
	v_pk_mul_f32 v[20:21], v[20:21], v[0:1] op_sel_hi:[1,0]
	v_pk_mul_f32 v[18:19], v[18:19], v[0:1] op_sel_hi:[1,0]
	v_pk_mul_f32 v[16:17], v[16:17], v[0:1] op_sel_hi:[1,0]
